# v35 + the 26 v_pk_mul_f32 in the mem_attn output normalisation (2 sites) and prep MFMA region split into single v_mul_f32 (7.5), bit-identical
# baseline (speedup 1.0000x reference)
.LBB0_1374:
	v_ashrrev_i32_e32 v71, 31, v70
	v_lshlrev_b64 v[0:1], 10, v[70:71]
	v_lshl_add_u64 v[4:5], v[72:73], 0, v[0:1]
	global_load_dwordx4 v[0:3], v[4:5], off
	global_load_dwordx4 v[100:103], v[4:5], off offset:64
	ds_read_b128 v[4:7], v87
	ds_read_b128 v[8:11], v87 offset:2048
	ds_read_b128 v[12:15], v88
	ds_read_b128 v[16:19], v88 offset:2048
	ds_read_b128 v[20:23], v87 offset:4096
	ds_read_b128 v[24:27], v87 offset:6144
	ds_read_b128 v[28:31], v88 offset:4096
	ds_read_b128 v[32:35], v88 offset:6144
	s_waitcnt vmcnt(1) lgkmcnt(7)
	v_mfma_f32_16x16x32_bf16 v[4:7], v[4:7], v[0:3], 0
	s_waitcnt vmcnt(0) lgkmcnt(5)
	v_mfma_f32_16x16x32_bf16 v[104:107], v[12:15], v[100:103], v[4:7]
	v_mfma_f32_16x16x32_bf16 v[4:7], v[8:11], v[0:3], 0
	s_waitcnt lgkmcnt(4)
	v_mfma_f32_16x16x32_bf16 v[108:111], v[16:19], v[100:103], v[4:7]
	s_waitcnt lgkmcnt(3)
	v_mfma_f32_16x16x32_bf16 v[4:7], v[20:23], v[0:3], 0
	s_waitcnt lgkmcnt(1)
	v_mfma_f32_16x16x32_bf16 v[52:55], v[28:31], v[100:103], v[4:7]
	v_mfma_f32_16x16x32_bf16 v[4:7], v[24:27], v[0:3], 0
	s_waitcnt lgkmcnt(0)
	v_mfma_f32_16x16x32_bf16 v[48:51], v[32:35], v[100:103], v[4:7]
	s_nop 5
	ds_read_b128 v[4:7], v87 offset:8192
	ds_read_b128 v[8:11], v87 offset:10240
	ds_read_b128 v[12:15], v88 offset:8192
	ds_read_b128 v[16:19], v88 offset:10240
	ds_read_b128 v[20:23], v87 offset:12288
	ds_read_b128 v[24:27], v87 offset:14336
	ds_read_b128 v[28:31], v88 offset:12288
	ds_read_b128 v[32:35], v88 offset:14336
	s_waitcnt lgkmcnt(7)
	v_mfma_f32_16x16x32_bf16 v[4:7], v[4:7], v[0:3], 0
	s_waitcnt lgkmcnt(5)
	v_mfma_f32_16x16x32_bf16 v[44:47], v[12:15], v[100:103], v[4:7]
	v_mfma_f32_16x16x32_bf16 v[4:7], v[8:11], v[0:3], 0
	s_waitcnt lgkmcnt(4)
	v_mfma_f32_16x16x32_bf16 v[40:43], v[16:19], v[100:103], v[4:7]
	s_waitcnt lgkmcnt(3)
	v_mfma_f32_16x16x32_bf16 v[4:7], v[20:23], v[0:3], 0
	s_waitcnt lgkmcnt(1)
	v_mfma_f32_16x16x32_bf16 v[36:39], v[28:31], v[100:103], v[4:7]
	v_mfma_f32_16x16x32_bf16 v[4:7], v[24:27], v[0:3], 0
	s_waitcnt lgkmcnt(0)
	v_mfma_f32_16x16x32_bf16 v[32:35], v[32:35], v[100:103], v[4:7]
	s_nop 5
	ds_read_b128 v[4:7], v87 offset:16384
	ds_read_b128 v[8:11], v87 offset:18432
	ds_read_b128 v[12:15], v88 offset:16384
	ds_read_b128 v[16:19], v88 offset:18432
	ds_read_b128 v[20:23], v87 offset:20480
	ds_read_b128 v[112:115], v87 offset:22528
	ds_read_b128 v[116:119], v88 offset:20480
	ds_read_b128 v[120:123], v88 offset:22528
	s_waitcnt lgkmcnt(7)
	v_mfma_f32_16x16x32_bf16 v[4:7], v[4:7], v[0:3], 0
	s_waitcnt lgkmcnt(5)
	v_mfma_f32_16x16x32_bf16 v[28:31], v[12:15], v[100:103], v[4:7]
	v_mfma_f32_16x16x32_bf16 v[4:7], v[8:11], v[0:3], 0
	s_waitcnt lgkmcnt(4)
	v_mfma_f32_16x16x32_bf16 v[24:27], v[16:19], v[100:103], v[4:7]
	s_waitcnt lgkmcnt(3)
	v_mfma_f32_16x16x32_bf16 v[4:7], v[20:23], v[0:3], 0
	s_waitcnt lgkmcnt(1)
	v_mfma_f32_16x16x32_bf16 v[20:23], v[116:119], v[100:103], v[4:7]
	v_mfma_f32_16x16x32_bf16 v[4:7], v[112:115], v[0:3], 0
	s_waitcnt lgkmcnt(0)
	v_mfma_f32_16x16x32_bf16 v[16:19], v[120:123], v[100:103], v[4:7]
	s_nop 5
	ds_read_b128 v[4:7], v87 offset:24576
	ds_read_b128 v[8:11], v87 offset:26624
	ds_read_b128 v[12:15], v88 offset:24576
	ds_read_b128 v[112:115], v88 offset:26624
	ds_read_b128 v[116:119], v87 offset:28672
	ds_read_b128 v[120:123], v87 offset:30720
	ds_read_b128 v[124:127], v88 offset:28672
	ds_read_b128 v[128:131], v88 offset:30720
	s_waitcnt lgkmcnt(7)
	v_mfma_f32_16x16x32_bf16 v[4:7], v[4:7], v[0:3], 0
	s_waitcnt lgkmcnt(5)
	v_mfma_f32_16x16x32_bf16 v[12:15], v[12:15], v[100:103], v[4:7]
	v_mfma_f32_16x16x32_bf16 v[4:7], v[8:11], v[0:3], 0
	s_waitcnt lgkmcnt(4)
	v_mfma_f32_16x16x32_bf16 v[8:11], v[112:115], v[100:103], v[4:7]
	s_waitcnt lgkmcnt(3)
	v_mfma_f32_16x16x32_bf16 v[4:7], v[116:119], v[0:3], 0
	s_waitcnt lgkmcnt(2)
	v_mfma_f32_16x16x32_bf16 v[0:3], v[120:123], v[0:3], 0
	s_waitcnt lgkmcnt(1)
	v_mfma_f32_16x16x32_bf16 v[4:7], v[124:127], v[100:103], v[4:7]
	s_waitcnt lgkmcnt(0)
	v_mfma_f32_16x16x32_bf16 v[0:3], v[128:131], v[100:103], v[0:3]
	v_max3_f32 v99, v104, s27, v105
	v_max3_f32 v99, v99, v106, v107
	v_max3_f32 v99, v99, v108, v109
	v_max3_f32 v99, v99, v110, v111
	v_max3_f32 v99, v99, v52, v53
	v_max3_f32 v99, v99, v54, v55
	v_max3_f32 v99, v99, v48, v49
	v_max3_f32 v99, v99, v50, v51
	v_max3_f32 v99, v99, v44, v45
	v_max3_f32 v99, v99, v46, v47
	v_max3_f32 v99, v99, v40, v41
	v_max3_f32 v99, v99, v42, v43
	v_max3_f32 v99, v99, v36, v37
	v_max3_f32 v99, v99, v38, v39
	v_max3_f32 v99, v99, v32, v33
	v_max3_f32 v99, v99, v34, v35
	v_max3_f32 v99, v99, v28, v29
	v_max3_f32 v99, v99, v30, v31
	v_max3_f32 v99, v99, v24, v25
	v_max3_f32 v99, v99, v26, v27
	v_max3_f32 v99, v99, v20, v21
	v_max3_f32 v99, v99, v22, v23
	v_max3_f32 v99, v99, v16, v17
	v_max3_f32 v99, v99, v18, v19
	v_max3_f32 v99, v99, v12, v13
	v_max3_f32 v99, v99, v14, v15
	v_max3_f32 v99, v99, v8, v9
	v_max3_f32 v99, v99, v10, v11
	v_max3_f32 v99, v99, v4, v5
	v_max3_f32 v99, v99, v6, v7
	v_max3_f32 v99, v99, v0, v1
	v_max3_f32 v99, v99, v2, v3
	ds_bpermute_b32 v100, v97, v99
	s_waitcnt lgkmcnt(0)
	v_max_f32_e32 v100, v100, v100
	v_max_f32_e32 v99, v99, v100
	ds_bpermute_b32 v100, v98, v99
	s_waitcnt lgkmcnt(0)
	v_max_f32_e32 v100, v100, v100
	v_max_f32_e32 v101, v99, v100
	v_sub_f32_e32 v99, v104, v101
	v_mul_f32_e32 v99, 0x3e38aa3b, v99
	v_sub_f32_e32 v100, v105, v101
	v_exp_f32_e32 v99, v99
	v_mul_f32_e32 v100, 0x3e38aa3b, v100
	v_exp_f32_e32 v100, v100
	v_sub_f32_e32 v52, v52, v101
	v_add_f32_e32 v102, 0, v99
	v_mul_f32_e32 v52, 0x3e38aa3b, v52
	v_add_f32_e32 v103, v100, v102
	v_sub_f32_e32 v102, v106, v101
	v_mul_f32_e32 v102, 0x3e38aa3b, v102
	v_exp_f32_e32 v102, v102
	v_sub_f32_e32 v53, v53, v101
	v_exp_f32_e32 v52, v52
	v_mul_f32_e32 v53, 0x3e38aa3b, v53
	v_add_f32_e32 v104, v102, v103
	v_sub_f32_e32 v103, v107, v101
	v_mul_f32_e32 v103, 0x3e38aa3b, v103
	v_exp_f32_e32 v103, v103
	v_sub_f32_e32 v54, v54, v101
	v_exp_f32_e32 v53, v53
	v_mul_f32_e32 v54, 0x3e38aa3b, v54
	v_add_f32_e32 v105, v103, v104
	v_sub_f32_e32 v104, v108, v101
	v_mul_f32_e32 v104, 0x3e38aa3b, v104
	v_exp_f32_e32 v104, v104
	v_sub_f32_e32 v55, v55, v101
	v_exp_f32_e32 v54, v54
	v_mul_f32_e32 v55, 0x3e38aa3b, v55
	v_add_f32_e32 v106, v104, v105
	v_sub_f32_e32 v105, v109, v101
	v_mul_f32_e32 v105, 0x3e38aa3b, v105
	v_exp_f32_e32 v105, v105
	v_sub_f32_e32 v48, v48, v101
	v_exp_f32_e32 v55, v55
	v_mul_f32_e32 v48, 0x3e38aa3b, v48
	v_add_f32_e32 v107, v105, v106
	v_sub_f32_e32 v106, v110, v101
	v_mul_f32_e32 v106, 0x3e38aa3b, v106
	v_exp_f32_e32 v106, v106
	v_sub_f32_e32 v49, v49, v101
	v_exp_f32_e32 v48, v48
	v_mul_f32_e32 v49, 0x3e38aa3b, v49
	v_add_f32_e32 v108, v106, v107
	v_sub_f32_e32 v107, v111, v101
	v_mul_f32_e32 v107, 0x3e38aa3b, v107
	v_exp_f32_e32 v107, v107
	v_sub_f32_e32 v50, v50, v101
	v_exp_f32_e32 v49, v49
	v_mul_f32_e32 v50, 0x3e38aa3b, v50
	v_add_f32_e32 v108, v107, v108
	v_add_f32_e32 v108, v52, v108
	v_add_f32_e32 v108, v53, v108
	v_sub_f32_e32 v51, v51, v101
	v_add_f32_e32 v108, v54, v108
	v_exp_f32_e32 v50, v50
	v_mul_f32_e32 v51, 0x3e38aa3b, v51
	v_sub_f32_e32 v44, v44, v101
	v_add_f32_e32 v108, v55, v108
	v_exp_f32_e32 v51, v51
	v_mul_f32_e32 v44, 0x3e38aa3b, v44
	v_sub_f32_e32 v45, v45, v101
	v_add_f32_e32 v108, v48, v108
	v_exp_f32_e32 v44, v44
	v_mul_f32_e32 v45, 0x3e38aa3b, v45
	v_sub_f32_e32 v46, v46, v101
	v_add_f32_e32 v108, v49, v108
	v_exp_f32_e32 v45, v45
	v_mul_f32_e32 v46, 0x3e38aa3b, v46
	v_sub_f32_e32 v47, v47, v101
	v_add_f32_e32 v108, v50, v108
	v_exp_f32_e32 v46, v46
	v_mul_f32_e32 v47, 0x3e38aa3b, v47
	v_sub_f32_e32 v40, v40, v101
	v_add_f32_e32 v108, v51, v108
	v_exp_f32_e32 v47, v47
	v_mul_f32_e32 v40, 0x3e38aa3b, v40
	v_sub_f32_e32 v41, v41, v101
	v_add_f32_e32 v108, v44, v108
	v_exp_f32_e32 v40, v40
	v_mul_f32_e32 v41, 0x3e38aa3b, v41
	v_sub_f32_e32 v42, v42, v101
	v_add_f32_e32 v108, v45, v108
	v_exp_f32_e32 v41, v41
	v_mul_f32_e32 v42, 0x3e38aa3b, v42
	v_sub_f32_e32 v43, v43, v101
	v_add_f32_e32 v108, v46, v108
	v_exp_f32_e32 v42, v42
	v_mul_f32_e32 v43, 0x3e38aa3b, v43
	v_sub_f32_e32 v36, v36, v101
	v_add_f32_e32 v108, v47, v108
	v_exp_f32_e32 v43, v43
	v_mul_f32_e32 v36, 0x3e38aa3b, v36
	v_sub_f32_e32 v37, v37, v101
	v_add_f32_e32 v108, v40, v108
	v_exp_f32_e32 v36, v36
	v_mul_f32_e32 v37, 0x3e38aa3b, v37
	v_sub_f32_e32 v38, v38, v101
	v_add_f32_e32 v108, v41, v108
	v_exp_f32_e32 v37, v37
	v_mul_f32_e32 v38, 0x3e38aa3b, v38
	v_sub_f32_e32 v39, v39, v101
	v_add_f32_e32 v108, v42, v108
	v_exp_f32_e32 v38, v38
	v_mul_f32_e32 v39, 0x3e38aa3b, v39
	v_sub_f32_e32 v32, v32, v101
	v_add_f32_e32 v108, v43, v108
	v_exp_f32_e32 v39, v39
	v_mul_f32_e32 v32, 0x3e38aa3b, v32
	v_sub_f32_e32 v33, v33, v101
	v_add_f32_e32 v108, v36, v108
	v_exp_f32_e32 v32, v32
	v_mul_f32_e32 v33, 0x3e38aa3b, v33
	v_sub_f32_e32 v34, v34, v101
	v_add_f32_e32 v108, v37, v108
	v_exp_f32_e32 v33, v33
	v_mul_f32_e32 v34, 0x3e38aa3b, v34
	v_sub_f32_e32 v35, v35, v101
	v_add_f32_e32 v108, v38, v108
	v_exp_f32_e32 v34, v34
	v_mul_f32_e32 v35, 0x3e38aa3b, v35
	v_sub_f32_e32 v28, v28, v101
	v_add_f32_e32 v108, v39, v108
	v_exp_f32_e32 v35, v35
	v_mul_f32_e32 v28, 0x3e38aa3b, v28
	v_sub_f32_e32 v29, v29, v101
	v_add_f32_e32 v108, v32, v108
	v_exp_f32_e32 v28, v28
	v_mul_f32_e32 v29, 0x3e38aa3b, v29
	v_sub_f32_e32 v30, v30, v101
	v_add_f32_e32 v108, v33, v108
	v_exp_f32_e32 v29, v29
	v_mul_f32_e32 v30, 0x3e38aa3b, v30
	v_sub_f32_e32 v31, v31, v101
	v_add_f32_e32 v108, v34, v108
	v_exp_f32_e32 v30, v30
	v_mul_f32_e32 v31, 0x3e38aa3b, v31
	v_sub_f32_e32 v24, v24, v101
	v_add_f32_e32 v108, v35, v108
	v_exp_f32_e32 v31, v31
	v_mul_f32_e32 v24, 0x3e38aa3b, v24
	v_add_f32_e32 v108, v28, v108
	v_exp_f32_e32 v109, v24
	v_add_f32_e32 v108, v29, v108
	v_add_f32_e32 v108, v30, v108
	v_sub_f32_e32 v25, v25, v101
	v_add_f32_e32 v108, v31, v108
	v_mul_f32_e32 v25, 0x3e38aa3b, v25
	v_add_f32_e32 v24, v109, v108
	v_exp_f32_e32 v108, v25
	v_sub_f32_e32 v25, v26, v101
	v_mul_f32_e32 v25, 0x3e38aa3b, v25
	v_exp_f32_e32 v110, v25
	v_sub_f32_e32 v25, v27, v101
	v_sub_f32_e32 v21, v21, v101
	v_mul_f32_e32 v25, 0x3e38aa3b, v25
	v_sub_f32_e32 v20, v20, v101
	v_mul_f32_e32 v21, 0x3e38aa3b, v21
	v_exp_f32_e32 v111, v25
	v_mul_f32_e32 v20, 0x3e38aa3b, v20
	v_exp_f32_e32 v113, v21
	v_sub_f32_e32 v21, v22, v101
	v_exp_f32_e32 v112, v20
	v_mul_f32_e32 v21, 0x3e38aa3b, v21
	v_add_f32_e32 v24, v108, v24
	v_exp_f32_e32 v114, v21
	v_sub_f32_e32 v21, v23, v101
	v_sub_f32_e32 v17, v17, v101
	v_add_f32_e32 v24, v110, v24
	v_mul_f32_e32 v21, 0x3e38aa3b, v21
	v_sub_f32_e32 v16, v16, v101
	v_mul_f32_e32 v17, 0x3e38aa3b, v17
	v_add_f32_e32 v24, v111, v24
	v_exp_f32_e32 v115, v21
	v_mul_f32_e32 v16, 0x3e38aa3b, v16
	v_exp_f32_e32 v117, v17
	v_sub_f32_e32 v17, v18, v101
	v_add_f32_e32 v20, v112, v24
	v_exp_f32_e32 v116, v16
	v_mul_f32_e32 v17, 0x3e38aa3b, v17
	v_add_f32_e32 v20, v113, v20
	v_exp_f32_e32 v118, v17
	v_sub_f32_e32 v17, v19, v101
	v_sub_f32_e32 v13, v13, v101
	v_add_f32_e32 v20, v114, v20
	v_mul_f32_e32 v17, 0x3e38aa3b, v17
	v_sub_f32_e32 v12, v12, v101
	v_mul_f32_e32 v13, 0x3e38aa3b, v13
	v_add_f32_e32 v20, v115, v20
	v_exp_f32_e32 v119, v17
	v_mul_f32_e32 v12, 0x3e38aa3b, v12
	v_exp_f32_e32 v121, v13
	v_sub_f32_e32 v13, v14, v101
	v_add_f32_e32 v16, v116, v20
	v_exp_f32_e32 v120, v12
	v_mul_f32_e32 v13, 0x3e38aa3b, v13
	v_add_f32_e32 v16, v117, v16
	v_exp_f32_e32 v122, v13
	v_sub_f32_e32 v13, v15, v101
	v_sub_f32_e32 v9, v9, v101
	v_add_f32_e32 v16, v118, v16
	v_mul_f32_e32 v13, 0x3e38aa3b, v13
	v_sub_f32_e32 v8, v8, v101
	v_mul_f32_e32 v9, 0x3e38aa3b, v9
	v_add_f32_e32 v16, v119, v16
	v_exp_f32_e32 v123, v13
	v_mul_f32_e32 v8, 0x3e38aa3b, v8
	v_exp_f32_e32 v125, v9
	v_sub_f32_e32 v9, v10, v101
	v_add_f32_e32 v12, v120, v16
	v_exp_f32_e32 v124, v8
	v_mul_f32_e32 v9, 0x3e38aa3b, v9
	v_add_f32_e32 v12, v121, v12
	v_exp_f32_e32 v126, v9
	v_sub_f32_e32 v9, v11, v101
	v_sub_f32_e32 v5, v5, v101
	v_add_f32_e32 v12, v122, v12
	v_mul_f32_e32 v9, 0x3e38aa3b, v9
	v_sub_f32_e32 v4, v4, v101
	v_mul_f32_e32 v5, 0x3e38aa3b, v5
	v_add_f32_e32 v12, v123, v12
	v_exp_f32_e32 v127, v9
	v_mul_f32_e32 v4, 0x3e38aa3b, v4
	v_exp_f32_e32 v129, v5
	v_sub_f32_e32 v5, v6, v101
	v_add_f32_e32 v8, v124, v12
	v_exp_f32_e32 v128, v4
	v_mul_f32_e32 v5, 0x3e38aa3b, v5
	v_add_f32_e32 v8, v125, v8
	v_exp_f32_e32 v130, v5
	v_sub_f32_e32 v5, v7, v101
	v_sub_f32_e32 v1, v1, v101
	v_add_f32_e32 v8, v126, v8
	v_mul_f32_e32 v5, 0x3e38aa3b, v5
	v_sub_f32_e32 v0, v0, v101
	v_mul_f32_e32 v1, 0x3e38aa3b, v1
	v_add_f32_e32 v8, v127, v8
	v_exp_f32_e32 v131, v5
	v_mul_f32_e32 v0, 0x3e38aa3b, v0
	v_exp_f32_e32 v133, v1
	v_sub_f32_e32 v1, v2, v101
	v_add_f32_e32 v4, v128, v8
	v_exp_f32_e32 v132, v0
	v_mul_f32_e32 v1, 0x3e38aa3b, v1
	v_add_f32_e32 v4, v129, v4
	v_exp_f32_e32 v134, v1
	v_sub_f32_e32 v1, v3, v101
	v_add_f32_e32 v4, v130, v4
	v_mul_f32_e32 v1, 0x3e38aa3b, v1
	v_add_f32_e32 v4, v131, v4
	v_exp_f32_e32 v101, v1
	v_add_f32_e32 v0, v132, v4
	v_add_f32_e32 v0, v133, v0
	v_add_f32_e32 v0, v134, v0
	v_add_f32_e32 v0, v101, v0
	ds_bpermute_b32 v1, v97, v0
	ds_read_b128 v[4:7], v89 offset:32768
	ds_read_b128 v[8:11], v89 offset:40960
	ds_read_b128 v[12:15], v89 offset:49152
	ds_read_b128 v[16:19], v89 offset:57344
	v_cvt_pk_bf16_f32 v2, v104, v105
	v_cvt_pk_bf16_f32 v3, v106, v107
	s_waitcnt lgkmcnt(4)
	v_add_f32_e32 v0, v0, v1
	ds_bpermute_b32 v1, v98, v0
	s_waitcnt lgkmcnt(0)
	v_add_f32_e32 v135, v0, v1
	v_cvt_pk_bf16_f32 v0, v99, v100
	v_cvt_pk_bf16_f32 v1, v102, v103
	s_nop 1
	v_mfma_f32_16x16x32_bf16 v[4:7], v[4:7], v[0:3], 0
	v_mfma_f32_16x16x32_bf16 v[8:11], v[8:11], v[0:3], 0
	v_mfma_f32_16x16x32_bf16 v[12:15], v[12:15], v[0:3], 0
	v_mfma_f32_16x16x32_bf16 v[0:3], v[16:19], v[0:3], 0
	v_cvt_pk_bf16_f32 v16, v52, v53
	v_cvt_pk_bf16_f32 v17, v54, v55
	v_cvt_pk_bf16_f32 v18, v48, v49
	v_cvt_pk_bf16_f32 v19, v50, v51
	ds_read_b128 v[20:23], v90 offset:32768
	ds_read_b128 v[24:27], v90 offset:40960
	ds_read_b128 v[48:51], v90 offset:49152
	ds_read_b128 v[52:55], v90 offset:57344
	s_waitcnt lgkmcnt(3)
	v_mfma_f32_16x16x32_bf16 v[4:7], v[20:23], v[16:19], v[4:7]
	s_waitcnt lgkmcnt(2)
	v_mfma_f32_16x16x32_bf16 v[8:11], v[24:27], v[16:19], v[8:11]
	s_waitcnt lgkmcnt(1)
	v_mfma_f32_16x16x32_bf16 v[12:15], v[48:51], v[16:19], v[12:15]
	s_waitcnt lgkmcnt(0)
	v_mfma_f32_16x16x32_bf16 v[0:3], v[52:55], v[16:19], v[0:3]
	v_cvt_pk_bf16_f32 v16, v44, v45
	v_cvt_pk_bf16_f32 v17, v46, v47
	v_cvt_pk_bf16_f32 v18, v40, v41
	v_cvt_pk_bf16_f32 v19, v42, v43
	ds_read_b128 v[20:23], v91 offset:32768
	ds_read_b128 v[24:27], v91 offset:40960
	ds_read_b128 v[40:43], v91 offset:49152
	ds_read_b128 v[44:47], v91 offset:57344
	s_waitcnt lgkmcnt(3)
	v_mfma_f32_16x16x32_bf16 v[4:7], v[20:23], v[16:19], v[4:7]
	s_waitcnt lgkmcnt(2)
	v_mfma_f32_16x16x32_bf16 v[8:11], v[24:27], v[16:19], v[8:11]
	s_waitcnt lgkmcnt(1)
	v_mfma_f32_16x16x32_bf16 v[12:15], v[40:43], v[16:19], v[12:15]
	s_waitcnt lgkmcnt(0)
	v_mfma_f32_16x16x32_bf16 v[0:3], v[44:47], v[16:19], v[0:3]
	v_cvt_pk_bf16_f32 v16, v36, v37
	v_cvt_pk_bf16_f32 v17, v38, v39
	v_cvt_pk_bf16_f32 v18, v32, v33
	v_cvt_pk_bf16_f32 v19, v34, v35
	ds_read_b128 v[20:23], v92 offset:32768
	ds_read_b128 v[24:27], v92 offset:40960
	ds_read_b128 v[32:35], v92 offset:49152
	ds_read_b128 v[36:39], v92 offset:57344
	s_waitcnt lgkmcnt(3)
	v_mfma_f32_16x16x32_bf16 v[4:7], v[20:23], v[16:19], v[4:7]
	s_waitcnt lgkmcnt(2)
	v_mfma_f32_16x16x32_bf16 v[8:11], v[24:27], v[16:19], v[8:11]
	s_waitcnt lgkmcnt(1)
	v_mfma_f32_16x16x32_bf16 v[12:15], v[32:35], v[16:19], v[12:15]
	s_waitcnt lgkmcnt(0)
	v_mfma_f32_16x16x32_bf16 v[0:3], v[36:39], v[16:19], v[0:3]
	v_cvt_pk_bf16_f32 v16, v28, v29
	v_cvt_pk_bf16_f32 v17, v30, v31
	ds_read_b128 v[20:23], v93 offset:32768
	ds_read_b128 v[24:27], v93 offset:40960
	ds_read_b128 v[28:31], v93 offset:49152
	ds_read_b128 v[32:35], v93 offset:57344
	v_cvt_pk_bf16_f32 v18, v109, v108
	v_cvt_pk_bf16_f32 v19, v110, v111
	s_waitcnt lgkmcnt(3)
	s_nop 0
	v_mfma_f32_16x16x32_bf16 v[4:7], v[20:23], v[16:19], v[4:7]
	s_waitcnt lgkmcnt(2)
	v_mfma_f32_16x16x32_bf16 v[8:11], v[24:27], v[16:19], v[8:11]
	s_waitcnt lgkmcnt(1)
	v_mfma_f32_16x16x32_bf16 v[12:15], v[28:31], v[16:19], v[12:15]
	s_waitcnt lgkmcnt(0)
	v_mfma_f32_16x16x32_bf16 v[0:3], v[32:35], v[16:19], v[0:3]
	ds_read_b128 v[20:23], v94 offset:32768
	ds_read_b128 v[24:27], v94 offset:40960
	ds_read_b128 v[28:31], v94 offset:49152
	ds_read_b128 v[32:35], v94 offset:57344
	v_cvt_pk_bf16_f32 v16, v112, v113
	v_cvt_pk_bf16_f32 v17, v114, v115
	v_cvt_pk_bf16_f32 v18, v116, v117
	v_cvt_pk_bf16_f32 v19, v118, v119
	s_waitcnt lgkmcnt(3)
	s_nop 0
	v_mfma_f32_16x16x32_bf16 v[4:7], v[20:23], v[16:19], v[4:7]
	s_waitcnt lgkmcnt(2)
	v_mfma_f32_16x16x32_bf16 v[8:11], v[24:27], v[16:19], v[8:11]
	s_waitcnt lgkmcnt(1)
	v_mfma_f32_16x16x32_bf16 v[12:15], v[28:31], v[16:19], v[12:15]
	s_waitcnt lgkmcnt(0)
	v_mfma_f32_16x16x32_bf16 v[0:3], v[32:35], v[16:19], v[0:3]
	ds_read_b128 v[20:23], v95 offset:32768
	ds_read_b128 v[24:27], v95 offset:40960
	ds_read_b128 v[28:31], v95 offset:49152
	ds_read_b128 v[32:35], v95 offset:57344
	v_cvt_pk_bf16_f32 v16, v120, v121
	v_cvt_pk_bf16_f32 v17, v122, v123
	v_cvt_pk_bf16_f32 v18, v124, v125
	v_cvt_pk_bf16_f32 v19, v126, v127
	s_waitcnt lgkmcnt(3)
	s_nop 0
	v_mfma_f32_16x16x32_bf16 v[4:7], v[20:23], v[16:19], v[4:7]
	s_waitcnt lgkmcnt(2)
	v_mfma_f32_16x16x32_bf16 v[8:11], v[24:27], v[16:19], v[8:11]
	s_waitcnt lgkmcnt(1)
	v_mfma_f32_16x16x32_bf16 v[12:15], v[28:31], v[16:19], v[12:15]
	s_waitcnt lgkmcnt(0)
	v_mfma_f32_16x16x32_bf16 v[0:3], v[32:35], v[16:19], v[0:3]
	ds_read_b128 v[20:23], v96 offset:32768
	ds_read_b128 v[24:27], v96 offset:40960
	ds_read_b128 v[28:31], v96 offset:49152
	ds_read_b128 v[32:35], v96 offset:57344
	v_cvt_pk_bf16_f32 v16, v128, v129
	v_cvt_pk_bf16_f32 v17, v130, v131
	v_cvt_pk_bf16_f32 v18, v132, v133
	v_cvt_pk_bf16_f32 v19, v134, v101
	s_waitcnt lgkmcnt(3)
	s_nop 0
	v_mfma_f32_16x16x32_bf16 v[4:7], v[20:23], v[16:19], v[4:7]
	s_waitcnt lgkmcnt(2)
	v_mfma_f32_16x16x32_bf16 v[8:11], v[24:27], v[16:19], v[8:11]
	s_waitcnt lgkmcnt(1)
	v_mfma_f32_16x16x32_bf16 v[12:15], v[28:31], v[16:19], v[12:15]
	s_waitcnt lgkmcnt(0)
	v_mfma_f32_16x16x32_bf16 v[0:3], v[32:35], v[16:19], v[0:3]
	v_div_scale_f32 v16, s[14:15], v135, v135, 1.0
	v_rcp_f32_e32 v17, v16
	v_div_scale_f32 v18, vcc, 1.0, v135, 1.0
	s_add_i32 s13, s13, 8
	v_fma_f32 v19, -v16, v17, 1.0
	v_fmac_f32_e32 v17, v19, v17
	v_mul_f32_e32 v19, v18, v17
	v_fma_f32 v20, -v16, v19, v18
	v_fmac_f32_e32 v19, v20, v17
	v_fma_f32 v16, -v16, v19, v18
	v_div_fmas_f32 v16, v16, v17, v19
	v_lshlrev_b64 v[18:19], 11, v[70:71]
	v_lshl_add_u64 v[18:19], s[4:5], 0, v[18:19]
	v_div_fixup_f32 v16, v16, v135, 1.0
	v_lshl_add_u64 v[18:19], v[18:19], 0, s[66:67]
	v_lshl_add_u64 v[18:19], v[18:19], 0, v[160:161]
	v_mul_f32_e32 v6, v6, v16
	v_mul_f32_e32 v7, v7, v16
	v_mul_f32_e32 v4, v4, v16
	v_mul_f32_e32 v5, v5, v16
	v_lshl_add_u64 v[20:21], v[18:19], 0, s[74:75]
	v_cvt_pk_bf16_f32 v4, v4, v5
	v_cvt_pk_bf16_f32 v5, v6, v7
	v_add_co_u32_e32 v6, vcc, s24, v18
	v_mul_f32_e32 v2, v2, v16
	v_mul_f32_e32 v3, v3, v16
	s_nop 0
	v_addc_co_u32_e32 v7, vcc, 0, v19, vcc
	global_store_dwordx2 v[6:7], v[4:5], off offset:1536
	v_mul_f32_e32 v4, v10, v16
	v_mul_f32_e32 v5, v11, v16
	v_mul_f32_e32 v6, v8, v16
	v_mul_f32_e32 v7, v9, v16
	v_mul_f32_e32 v0, v0, v16
	v_mul_f32_e32 v1, v1, v16
	v_cvt_pk_bf16_f32 v6, v6, v7
	v_cvt_pk_bf16_f32 v7, v4, v5
	global_store_dwordx2 v[20:21], v[6:7], off offset:32
	v_mul_f32_e32 v4, v14, v16
	v_mul_f32_e32 v5, v15, v16
	v_mul_f32_e32 v6, v12, v16
	v_mul_f32_e32 v7, v13, v16
	v_cvt_pk_bf16_f32 v0, v0, v1
	v_cvt_pk_bf16_f32 v6, v6, v7
	v_cvt_pk_bf16_f32 v7, v4, v5
	v_cvt_pk_bf16_f32 v1, v2, v3
	s_cmp_gt_i32 s13, 7
	v_add_u32_e32 v70, 0x80, v70
	global_store_dwordx2 v[20:21], v[6:7], off offset:64
	global_store_dwordx2 v[20:21], v[0:1], off offset:96
	s_cbranch_scc0 .LBB0_1374
	s_branch .LBB0_1371

.LBB0_1748:
	ds_read_b32 v30, v73 offset:24576
	ds_read_b64 v[22:23], v74 offset:24576
	ds_read_b32 v31, v75 offset:24576
	ds_read_b32 v32, v76 offset:24576
	s_and_b64 vcc, exec, s[4:5]
	s_waitcnt lgkmcnt(2)
	v_sub_f32_e32 v22, v30, v22
	v_sub_f32_e32 v23, v30, v23
	v_mul_f32_e32 v22, 0x3fb8aa3b, v22
	v_exp_f32_e32 v24, v22
	v_mul_f32_e32 v22, 0x3fb8aa3b, v23
	v_exp_f32_e32 v25, v22
	s_waitcnt lgkmcnt(1)
	v_sub_f32_e32 v22, v30, v31
	s_waitcnt lgkmcnt(0)
	v_sub_f32_e32 v23, v30, v32
	v_mul_f32_e32 v22, 0x3fb8aa3b, v22
	v_mul_f32_e32 v23, 0x3fb8aa3b, v23
	v_exp_f32_e32 v22, v22
	v_exp_f32_e32 v23, v23
	s_cbranch_vccnz .LBB0_1750
	ds_read_b32 v30, v73 offset:24832
	v_readlane_b32 s0, v246, 10
	v_readlane_b32 s1, v246, 11
	s_waitcnt lgkmcnt(0)
	v_mul_f32_e32 v6, v6, v30
	v_mul_f32_e32 v7, v7, v30
	s_nop 0
	v_mul_f32_e32 v6, v22, v6
	v_mul_f32_e32 v7, v23, v7
	v_mul_f32_e32 v4, v4, v30
	v_mul_f32_e32 v5, v5, v30
	v_cndmask_b32_e64 v7, 0, v7, s[0:1]
	v_readlane_b32 s0, v246, 12
	v_readlane_b32 s1, v246, 13
	v_mul_f32_e32 v4, v24, v4
	v_mul_f32_e32 v5, v25, v5
	s_nop 0
	v_cndmask_b32_e64 v6, 0, v6, s[0:1]
	v_readlane_b32 s0, v246, 8
	v_readlane_b32 s1, v246, 9
	s_nop 1
	v_cndmask_b32_e64 v5, 0, v5, s[0:1]
	v_readlane_b32 s0, v247, 53
	v_readlane_b32 s1, v247, 54
	s_nop 1
	v_cndmask_b32_e64 v4, 0, v4, s[0:1]
	ds_write_b128 v190, v[4:7]
.LBB0_1750:
	v_readlane_b32 s0, v247, 51
	v_mul_f32_e32 v4, v0, v24
	v_readlane_b32 s1, v247, 52
	v_mul_f32_e32 v1, v1, v25
	v_mul_f32_e32 v2, v2, v22
	v_mul_f32_e32 v3, v3, v23
	v_cndmask_b32_e64 v4, v4, 0, s[0:1]
	v_readlane_b32 s0, v247, 53
	v_readlane_b32 s1, v247, 54
	v_readlane_b32 s8, v247, 59
	v_readlane_b32 s9, v247, 60
	v_cndmask_b32_e64 v1, 0, v1, s[0:1]
	s_lshl_b32 s0, s30, 8
	s_add_i32 s0, s0, s13
	s_ashr_i32 s1, s0, 31
	s_lshl_b64 s[4:5], s[0:1], 13
	v_lshl_add_u64 v[22:23], v[10:11], 0, s[4:5]
	v_readlane_b32 s4, v247, 57
	v_cvt_pk_bf16_f32 v4, v4, v1
	v_cvt_pk_bf16_f32 v1, v2, v3
	v_readlane_b32 s5, v247, 58
	v_mov_b32_e32 v0, 0
	s_andn2_b64 vcc, exec, s[8:9]
	v_cndmask_b32_e64 v2, v1, 0, s[4:5]
	v_readlane_b32 s4, v247, 55
	v_lshrrev_b32_e32 v1, 16, v1
	v_readlane_b32 s5, v247, 56
	v_mov_b32_e32 v6, 0
	v_mov_b32_e32 v7, 0
	v_cndmask_b32_e64 v1, v1, 0, s[4:5]
	v_perm_b32 v5, v1, v2, s14
	v_lshl_add_u64 v[2:3], v[12:13], 1, v[22:23]
	v_cndmask_b32_e64 v1, 0, 1, s[8:9]
	global_store_dwordx2 v[2:3], v[4:5], off
	v_cmp_ne_u32_e64 s[4:5], 1, v1
	v_mov_b32_e32 v1, 0
	v_mov_b32_e32 v2, 0
	v_mov_b32_e32 v3, 0
	v_mov_b32_e32 v4, 0
	v_mov_b32_e32 v5, 0
	s_cbranch_vccnz .LBB0_1752
	ds_read_b128 v[0:3], v29 offset:49152
	ds_read_b128 v[4:7], v191 offset:49152
	ds_read_b128 v[30:33], v191 offset:32768
	s_waitcnt lgkmcnt(1)
	v_mfma_f32_16x16x32_bf16 v[4:7], v[0:3], v[4:7], 0
	s_waitcnt lgkmcnt(0)
	v_mfma_f32_16x16x32_bf16 v[0:3], v[0:3], v[30:33], 0
	ds_read_b128 v[28:31], v28 offset:49152
	ds_read_b128 v[32:35], v192 offset:49152
	ds_read_b128 v[36:39], v192 offset:32768
	s_waitcnt lgkmcnt(1)
	v_mfma_f32_16x16x32_bf16 v[4:7], v[28:31], v[32:35], v[4:7]
	s_waitcnt lgkmcnt(0)
	v_mfma_f32_16x16x32_bf16 v[0:3], v[28:31], v[36:39], v[0:3]
	ds_read_b128 v[28:31], v27 offset:49152
	ds_read_b128 v[32:35], v193 offset:49152
	ds_read_b128 v[36:39], v193 offset:32768
	s_waitcnt lgkmcnt(1)
	v_mfma_f32_16x16x32_bf16 v[4:7], v[28:31], v[32:35], v[4:7]
	s_waitcnt lgkmcnt(0)
	v_mfma_f32_16x16x32_bf16 v[0:3], v[28:31], v[36:39], v[0:3]
	ds_read_b128 v[24:27], v26 offset:49152
	ds_read_b128 v[28:31], v194 offset:49152
	ds_read_b128 v[32:35], v194 offset:32768
	s_waitcnt lgkmcnt(1)
	v_mfma_f32_16x16x32_bf16 v[4:7], v[24:27], v[28:31], v[4:7]
	s_waitcnt lgkmcnt(0)
	v_mfma_f32_16x16x32_bf16 v[0:3], v[24:27], v[32:35], v[0:3]
.LBB0_1752:
	ds_read_b32 v28, v77 offset:24576
	ds_read_b64 v[24:25], v74 offset:24576
	ds_read_b32 v29, v75 offset:24576
	ds_read_b32 v30, v76 offset:24576
	s_and_b64 vcc, exec, s[4:5]
	s_waitcnt lgkmcnt(2)
	v_sub_f32_e32 v24, v28, v24
	v_sub_f32_e32 v25, v28, v25
	v_mul_f32_e32 v24, 0x3fb8aa3b, v24
	v_exp_f32_e32 v26, v24
	v_mul_f32_e32 v24, 0x3fb8aa3b, v25
	v_exp_f32_e32 v27, v24
	s_waitcnt lgkmcnt(1)
	v_sub_f32_e32 v24, v28, v29
	s_waitcnt lgkmcnt(0)
	v_sub_f32_e32 v25, v28, v30
	v_mul_f32_e32 v24, 0x3fb8aa3b, v24
	v_mul_f32_e32 v25, 0x3fb8aa3b, v25
	v_exp_f32_e32 v24, v24
	v_exp_f32_e32 v25, v25
	s_cbranch_vccnz .LBB0_1754
	ds_read_b32 v28, v77 offset:24832
	v_readlane_b32 s4, v246, 16
	v_readlane_b32 s5, v246, 17
	s_waitcnt lgkmcnt(0)
	v_mul_f32_e32 v6, v6, v28
	v_mul_f32_e32 v7, v7, v28
	s_nop 0
	v_mul_f32_e32 v6, v24, v6
	v_mul_f32_e32 v7, v25, v7
	v_mul_f32_e32 v4, v4, v28
	v_mul_f32_e32 v5, v5, v28
	v_cndmask_b32_e64 v7, 0, v7, s[4:5]
	v_readlane_b32 s4, v246, 18
	v_readlane_b32 s5, v246, 19
	v_mul_f32_e32 v4, v26, v4
	v_mul_f32_e32 v5, v27, v5
	s_nop 0
	v_cndmask_b32_e64 v6, 0, v6, s[4:5]
	v_readlane_b32 s4, v246, 14
	v_readlane_b32 s5, v246, 15
	s_nop 1
	v_cndmask_b32_e64 v5, 0, v5, s[4:5]
	v_readlane_b32 s4, v247, 63
	v_readlane_b32 s5, v246, 0
	s_nop 1
	v_cndmask_b32_e64 v4, 0, v4, s[4:5]
	ds_write_b128 v195, v[4:7]
.LBB0_1754:
	v_readlane_b32 s4, v247, 61
	v_mul_f32_e32 v0, v0, v26
	v_readlane_b32 s5, v247, 62
	v_readlane_b32 s8, v247, 46
	v_readlane_b32 s9, v247, 47
	v_cndmask_b32_e64 v4, v0, 0, s[4:5]
	v_readlane_b32 s4, v247, 63
	v_mul_f32_e32 v0, v1, v27
	v_readlane_b32 s5, v246, 0
	s_and_b64 vcc, exec, s[8:9]
	s_nop 0
	v_cndmask_b32_e64 v5, 0, v0, s[4:5]
	v_mul_f32_e32 v0, v2, v24
	v_mul_f32_e32 v1, v3, v25
	v_readlane_b32 s4, v246, 3
	v_cvt_pk_bf16_f32 v0, v0, v1
	v_readlane_b32 s5, v246, 4
	v_cvt_pk_bf16_f32 v2, v4, v5
	s_nop 0
	v_cndmask_b32_e64 v1, v0, 0, s[4:5]
	v_readlane_b32 s4, v246, 1
	v_lshrrev_b32_e32 v0, 16, v0
	v_readlane_b32 s5, v246, 2
	s_nop 1
	v_cndmask_b32_e64 v0, v0, 0, s[4:5]
	v_perm_b32 v3, v0, v1, s14
	v_lshl_add_u64 v[0:1], v[14:15], 1, v[22:23]
	s_mov_b64 s[4:5], -1
	global_store_dwordx2 v[0:1], v[2:3], off
	s_waitcnt lgkmcnt(0)
	s_barrier
	s_cbranch_vccz .LBB0_1761
	v_readlane_b32 s8, v246, 5
	v_readlane_b32 s9, v246, 6
	s_and_saveexec_b64 s[4:5], s[8:9]
	s_cbranch_execz .LBB0_1760
	s_lshl_b64 s[30:31], s[0:1], 14
	v_readlane_b32 s8, v247, 40
	s_add_u32 s34, s8, s30
	v_readlane_b32 s8, v247, 41
	s_addc_u32 s35, s8, s31
	s_mov_b64 s[36:37], 0
	v_mov_b32_e32 v0, v181
	v_mov_b32_e32 v1, v180
	v_mov_b32_e32 v2, v179

.LBB0_1769:
	v_mad_i64_i32 v[4:5], s[12:13], v70, s14, v[72:73]
	global_load_dwordx4 v[0:3], v[4:5], off
	global_load_dwordx4 v[100:103], v[4:5], off offset:64
	ds_read_b128 v[4:7], v87
	ds_read_b128 v[8:11], v87 offset:2048
	ds_read_b128 v[12:15], v88
	ds_read_b128 v[16:19], v88 offset:2048
	ds_read_b128 v[20:23], v87 offset:4096
	ds_read_b128 v[24:27], v87 offset:6144
	ds_read_b128 v[28:31], v88 offset:4096
	ds_read_b128 v[32:35], v88 offset:6144
	v_ashrrev_i32_e32 v71, 31, v70
	s_waitcnt vmcnt(1) lgkmcnt(7)
	v_mfma_f32_16x16x32_bf16 v[4:7], v[4:7], v[0:3], 0
	s_waitcnt vmcnt(0) lgkmcnt(5)
	v_mfma_f32_16x16x32_bf16 v[104:107], v[12:15], v[100:103], v[4:7]
	v_mfma_f32_16x16x32_bf16 v[4:7], v[8:11], v[0:3], 0
	s_waitcnt lgkmcnt(4)
	v_mfma_f32_16x16x32_bf16 v[108:111], v[16:19], v[100:103], v[4:7]
	s_waitcnt lgkmcnt(3)
	v_mfma_f32_16x16x32_bf16 v[4:7], v[20:23], v[0:3], 0
	s_waitcnt lgkmcnt(1)
	v_mfma_f32_16x16x32_bf16 v[52:55], v[28:31], v[100:103], v[4:7]
	v_mfma_f32_16x16x32_bf16 v[4:7], v[24:27], v[0:3], 0
	s_waitcnt lgkmcnt(0)
	v_mfma_f32_16x16x32_bf16 v[48:51], v[32:35], v[100:103], v[4:7]
	s_nop 5
	ds_read_b128 v[4:7], v87 offset:8192
	ds_read_b128 v[8:11], v87 offset:10240
	ds_read_b128 v[12:15], v88 offset:8192
	ds_read_b128 v[16:19], v88 offset:10240
	ds_read_b128 v[20:23], v87 offset:12288
	ds_read_b128 v[24:27], v87 offset:14336
	ds_read_b128 v[28:31], v88 offset:12288
	ds_read_b128 v[32:35], v88 offset:14336
	s_waitcnt lgkmcnt(7)
	v_mfma_f32_16x16x32_bf16 v[4:7], v[4:7], v[0:3], 0
	s_waitcnt lgkmcnt(5)
	v_mfma_f32_16x16x32_bf16 v[44:47], v[12:15], v[100:103], v[4:7]
	v_mfma_f32_16x16x32_bf16 v[4:7], v[8:11], v[0:3], 0
	s_waitcnt lgkmcnt(4)
	v_mfma_f32_16x16x32_bf16 v[40:43], v[16:19], v[100:103], v[4:7]
	s_waitcnt lgkmcnt(3)
	v_mfma_f32_16x16x32_bf16 v[4:7], v[20:23], v[0:3], 0
	s_waitcnt lgkmcnt(1)
	v_mfma_f32_16x16x32_bf16 v[36:39], v[28:31], v[100:103], v[4:7]
	v_mfma_f32_16x16x32_bf16 v[4:7], v[24:27], v[0:3], 0
	s_waitcnt lgkmcnt(0)
	v_mfma_f32_16x16x32_bf16 v[32:35], v[32:35], v[100:103], v[4:7]
	s_nop 5
	ds_read_b128 v[4:7], v87 offset:16384
	ds_read_b128 v[8:11], v87 offset:18432
	ds_read_b128 v[12:15], v88 offset:16384
	ds_read_b128 v[16:19], v88 offset:18432
	ds_read_b128 v[20:23], v87 offset:20480
	ds_read_b128 v[112:115], v87 offset:22528
	ds_read_b128 v[116:119], v88 offset:20480
	ds_read_b128 v[120:123], v88 offset:22528
	s_waitcnt lgkmcnt(7)
	v_mfma_f32_16x16x32_bf16 v[4:7], v[4:7], v[0:3], 0
	s_waitcnt lgkmcnt(5)
	v_mfma_f32_16x16x32_bf16 v[28:31], v[12:15], v[100:103], v[4:7]
	v_mfma_f32_16x16x32_bf16 v[4:7], v[8:11], v[0:3], 0
	s_waitcnt lgkmcnt(4)
	v_mfma_f32_16x16x32_bf16 v[24:27], v[16:19], v[100:103], v[4:7]
	s_waitcnt lgkmcnt(3)
	v_mfma_f32_16x16x32_bf16 v[4:7], v[20:23], v[0:3], 0
	s_waitcnt lgkmcnt(1)
	v_mfma_f32_16x16x32_bf16 v[20:23], v[116:119], v[100:103], v[4:7]
	v_mfma_f32_16x16x32_bf16 v[4:7], v[112:115], v[0:3], 0
	s_waitcnt lgkmcnt(0)
	v_mfma_f32_16x16x32_bf16 v[16:19], v[120:123], v[100:103], v[4:7]
	s_nop 5
	ds_read_b128 v[4:7], v87 offset:24576
	ds_read_b128 v[8:11], v87 offset:26624
	ds_read_b128 v[12:15], v88 offset:24576
	ds_read_b128 v[112:115], v88 offset:26624
	ds_read_b128 v[116:119], v87 offset:28672
	ds_read_b128 v[120:123], v87 offset:30720
	ds_read_b128 v[124:127], v88 offset:28672
	ds_read_b128 v[128:131], v88 offset:30720
	s_waitcnt lgkmcnt(7)
	v_mfma_f32_16x16x32_bf16 v[4:7], v[4:7], v[0:3], 0
	s_waitcnt lgkmcnt(5)
	v_mfma_f32_16x16x32_bf16 v[12:15], v[12:15], v[100:103], v[4:7]
	v_mfma_f32_16x16x32_bf16 v[4:7], v[8:11], v[0:3], 0
	s_waitcnt lgkmcnt(4)
	v_mfma_f32_16x16x32_bf16 v[8:11], v[112:115], v[100:103], v[4:7]
	s_waitcnt lgkmcnt(3)
	v_mfma_f32_16x16x32_bf16 v[4:7], v[116:119], v[0:3], 0
	s_waitcnt lgkmcnt(2)
	v_mfma_f32_16x16x32_bf16 v[0:3], v[120:123], v[0:3], 0
	s_waitcnt lgkmcnt(1)
	v_mfma_f32_16x16x32_bf16 v[4:7], v[124:127], v[100:103], v[4:7]
	s_waitcnt lgkmcnt(0)
	v_mfma_f32_16x16x32_bf16 v[0:3], v[128:131], v[100:103], v[0:3]
	v_max3_f32 v99, v104, s27, v105
	v_max3_f32 v99, v99, v106, v107
	v_max3_f32 v99, v99, v108, v109
	v_max3_f32 v99, v99, v110, v111
	v_max3_f32 v99, v99, v52, v53
	v_max3_f32 v99, v99, v54, v55
	v_max3_f32 v99, v99, v48, v49
	v_max3_f32 v99, v99, v50, v51
	v_max3_f32 v99, v99, v44, v45
	v_max3_f32 v99, v99, v46, v47
	v_max3_f32 v99, v99, v40, v41
	v_max3_f32 v99, v99, v42, v43
	v_max3_f32 v99, v99, v36, v37
	v_max3_f32 v99, v99, v38, v39
	v_max3_f32 v99, v99, v32, v33
	v_max3_f32 v99, v99, v34, v35
	v_max3_f32 v99, v99, v28, v29
	v_max3_f32 v99, v99, v30, v31
	v_max3_f32 v99, v99, v24, v25
	v_max3_f32 v99, v99, v26, v27
	v_max3_f32 v99, v99, v20, v21
	v_max3_f32 v99, v99, v22, v23
	v_max3_f32 v99, v99, v16, v17
	v_max3_f32 v99, v99, v18, v19
	v_max3_f32 v99, v99, v12, v13
	v_max3_f32 v99, v99, v14, v15
	v_max3_f32 v99, v99, v8, v9
	v_max3_f32 v99, v99, v10, v11
	v_max3_f32 v99, v99, v4, v5
	v_max3_f32 v99, v99, v6, v7
	v_max3_f32 v99, v99, v0, v1
	v_max3_f32 v99, v99, v2, v3
	ds_bpermute_b32 v100, v97, v99
	s_waitcnt lgkmcnt(0)
	v_max_f32_e32 v100, v100, v100
	v_max_f32_e32 v99, v99, v100
	ds_bpermute_b32 v100, v98, v99
	s_waitcnt lgkmcnt(0)
	v_max_f32_e32 v100, v100, v100
	v_max_f32_e32 v101, v99, v100
	v_sub_f32_e32 v99, v104, v101
	v_mul_f32_e32 v99, 0x3e38aa3b, v99
	v_sub_f32_e32 v100, v105, v101
	v_exp_f32_e32 v99, v99
	v_mul_f32_e32 v100, 0x3e38aa3b, v100
	v_exp_f32_e32 v100, v100
	v_sub_f32_e32 v52, v52, v101
	v_add_f32_e32 v102, 0, v99
	v_mul_f32_e32 v52, 0x3e38aa3b, v52
	v_add_f32_e32 v103, v100, v102
	v_sub_f32_e32 v102, v106, v101
	v_mul_f32_e32 v102, 0x3e38aa3b, v102
	v_exp_f32_e32 v102, v102
	v_sub_f32_e32 v53, v53, v101
	v_exp_f32_e32 v52, v52
	v_mul_f32_e32 v53, 0x3e38aa3b, v53
	v_add_f32_e32 v104, v102, v103
	v_sub_f32_e32 v103, v107, v101
	v_mul_f32_e32 v103, 0x3e38aa3b, v103
	v_exp_f32_e32 v103, v103
	v_sub_f32_e32 v54, v54, v101
	v_exp_f32_e32 v53, v53
	v_mul_f32_e32 v54, 0x3e38aa3b, v54
	v_add_f32_e32 v105, v103, v104
	v_sub_f32_e32 v104, v108, v101
	v_mul_f32_e32 v104, 0x3e38aa3b, v104
	v_exp_f32_e32 v104, v104
	v_sub_f32_e32 v55, v55, v101
	v_exp_f32_e32 v54, v54
	v_mul_f32_e32 v55, 0x3e38aa3b, v55
	v_add_f32_e32 v106, v104, v105
	v_sub_f32_e32 v105, v109, v101
	v_mul_f32_e32 v105, 0x3e38aa3b, v105
	v_exp_f32_e32 v105, v105
	v_sub_f32_e32 v48, v48, v101
	v_exp_f32_e32 v55, v55
	v_mul_f32_e32 v48, 0x3e38aa3b, v48
	v_add_f32_e32 v107, v105, v106
	v_sub_f32_e32 v106, v110, v101
	v_mul_f32_e32 v106, 0x3e38aa3b, v106
	v_exp_f32_e32 v106, v106
	v_sub_f32_e32 v49, v49, v101
	v_exp_f32_e32 v48, v48
	v_mul_f32_e32 v49, 0x3e38aa3b, v49
	v_add_f32_e32 v108, v106, v107
	v_sub_f32_e32 v107, v111, v101
	v_mul_f32_e32 v107, 0x3e38aa3b, v107
	v_exp_f32_e32 v107, v107
	v_sub_f32_e32 v50, v50, v101
	v_exp_f32_e32 v49, v49
	v_mul_f32_e32 v50, 0x3e38aa3b, v50
	v_add_f32_e32 v108, v107, v108
	v_add_f32_e32 v108, v52, v108
	v_add_f32_e32 v108, v53, v108
	v_sub_f32_e32 v51, v51, v101
	v_add_f32_e32 v108, v54, v108
	v_exp_f32_e32 v50, v50
	v_mul_f32_e32 v51, 0x3e38aa3b, v51
	v_sub_f32_e32 v44, v44, v101
	v_add_f32_e32 v108, v55, v108
	v_exp_f32_e32 v51, v51
	v_mul_f32_e32 v44, 0x3e38aa3b, v44
	v_sub_f32_e32 v45, v45, v101
	v_add_f32_e32 v108, v48, v108
	v_exp_f32_e32 v44, v44
	v_mul_f32_e32 v45, 0x3e38aa3b, v45
	v_sub_f32_e32 v46, v46, v101
	v_add_f32_e32 v108, v49, v108
	v_exp_f32_e32 v45, v45
	v_mul_f32_e32 v46, 0x3e38aa3b, v46
	v_sub_f32_e32 v47, v47, v101
	v_add_f32_e32 v108, v50, v108
	v_exp_f32_e32 v46, v46
	v_mul_f32_e32 v47, 0x3e38aa3b, v47
	v_sub_f32_e32 v40, v40, v101
	v_add_f32_e32 v108, v51, v108
	v_exp_f32_e32 v47, v47
	v_mul_f32_e32 v40, 0x3e38aa3b, v40
	v_sub_f32_e32 v41, v41, v101
	v_add_f32_e32 v108, v44, v108
	v_exp_f32_e32 v40, v40
	v_mul_f32_e32 v41, 0x3e38aa3b, v41
	v_sub_f32_e32 v42, v42, v101
	v_add_f32_e32 v108, v45, v108
	v_exp_f32_e32 v41, v41
	v_mul_f32_e32 v42, 0x3e38aa3b, v42
	v_sub_f32_e32 v43, v43, v101
	v_add_f32_e32 v108, v46, v108
	v_exp_f32_e32 v42, v42
	v_mul_f32_e32 v43, 0x3e38aa3b, v43
	v_sub_f32_e32 v36, v36, v101
	v_add_f32_e32 v108, v47, v108
	v_exp_f32_e32 v43, v43
	v_mul_f32_e32 v36, 0x3e38aa3b, v36
	v_sub_f32_e32 v37, v37, v101
	v_add_f32_e32 v108, v40, v108
	v_exp_f32_e32 v36, v36
	v_mul_f32_e32 v37, 0x3e38aa3b, v37
	v_sub_f32_e32 v38, v38, v101
	v_add_f32_e32 v108, v41, v108
	v_exp_f32_e32 v37, v37
	v_mul_f32_e32 v38, 0x3e38aa3b, v38
	v_sub_f32_e32 v39, v39, v101
	v_add_f32_e32 v108, v42, v108
	v_exp_f32_e32 v38, v38
	v_mul_f32_e32 v39, 0x3e38aa3b, v39
	v_sub_f32_e32 v32, v32, v101
	v_add_f32_e32 v108, v43, v108
	v_exp_f32_e32 v39, v39
	v_mul_f32_e32 v32, 0x3e38aa3b, v32
	v_sub_f32_e32 v33, v33, v101
	v_add_f32_e32 v108, v36, v108
	v_exp_f32_e32 v32, v32
	v_mul_f32_e32 v33, 0x3e38aa3b, v33
	v_sub_f32_e32 v34, v34, v101
	v_add_f32_e32 v108, v37, v108
	v_exp_f32_e32 v33, v33
	v_mul_f32_e32 v34, 0x3e38aa3b, v34
	v_sub_f32_e32 v35, v35, v101
	v_add_f32_e32 v108, v38, v108
	v_exp_f32_e32 v34, v34
	v_mul_f32_e32 v35, 0x3e38aa3b, v35
	v_sub_f32_e32 v28, v28, v101
	v_add_f32_e32 v108, v39, v108
	v_exp_f32_e32 v35, v35
	v_mul_f32_e32 v28, 0x3e38aa3b, v28
	v_sub_f32_e32 v29, v29, v101
	v_add_f32_e32 v108, v32, v108
	v_exp_f32_e32 v28, v28
	v_mul_f32_e32 v29, 0x3e38aa3b, v29
	v_sub_f32_e32 v30, v30, v101
	v_add_f32_e32 v108, v33, v108
	v_exp_f32_e32 v29, v29
	v_mul_f32_e32 v30, 0x3e38aa3b, v30
	v_sub_f32_e32 v31, v31, v101
	v_add_f32_e32 v108, v34, v108
	v_exp_f32_e32 v30, v30
	v_mul_f32_e32 v31, 0x3e38aa3b, v31
	v_sub_f32_e32 v24, v24, v101
	v_add_f32_e32 v108, v35, v108
	v_exp_f32_e32 v31, v31
	v_mul_f32_e32 v24, 0x3e38aa3b, v24
	v_add_f32_e32 v108, v28, v108
	v_exp_f32_e32 v109, v24
	v_add_f32_e32 v108, v29, v108
	v_add_f32_e32 v108, v30, v108
	v_sub_f32_e32 v25, v25, v101
	v_add_f32_e32 v108, v31, v108
	v_mul_f32_e32 v25, 0x3e38aa3b, v25
	v_add_f32_e32 v24, v109, v108
	v_exp_f32_e32 v108, v25
	v_sub_f32_e32 v25, v26, v101
	v_mul_f32_e32 v25, 0x3e38aa3b, v25
	v_exp_f32_e32 v110, v25
	v_sub_f32_e32 v25, v27, v101
	v_sub_f32_e32 v21, v21, v101
	v_mul_f32_e32 v25, 0x3e38aa3b, v25
	v_sub_f32_e32 v20, v20, v101
	v_mul_f32_e32 v21, 0x3e38aa3b, v21
	v_exp_f32_e32 v111, v25
	v_mul_f32_e32 v20, 0x3e38aa3b, v20
	v_exp_f32_e32 v113, v21
	v_sub_f32_e32 v21, v22, v101
	v_exp_f32_e32 v112, v20
	v_mul_f32_e32 v21, 0x3e38aa3b, v21
	v_add_f32_e32 v24, v108, v24
	v_exp_f32_e32 v114, v21
	v_sub_f32_e32 v21, v23, v101
	v_sub_f32_e32 v17, v17, v101
	v_add_f32_e32 v24, v110, v24
	v_mul_f32_e32 v21, 0x3e38aa3b, v21
	v_sub_f32_e32 v16, v16, v101
	v_mul_f32_e32 v17, 0x3e38aa3b, v17
	v_add_f32_e32 v24, v111, v24
	v_exp_f32_e32 v115, v21
	v_mul_f32_e32 v16, 0x3e38aa3b, v16
	v_exp_f32_e32 v117, v17
	v_sub_f32_e32 v17, v18, v101
	v_add_f32_e32 v20, v112, v24
	v_exp_f32_e32 v116, v16
	v_mul_f32_e32 v17, 0x3e38aa3b, v17
	v_add_f32_e32 v20, v113, v20
	v_exp_f32_e32 v118, v17
	v_sub_f32_e32 v17, v19, v101
	v_sub_f32_e32 v13, v13, v101
	v_add_f32_e32 v20, v114, v20
	v_mul_f32_e32 v17, 0x3e38aa3b, v17
	v_sub_f32_e32 v12, v12, v101
	v_mul_f32_e32 v13, 0x3e38aa3b, v13
	v_add_f32_e32 v20, v115, v20
	v_exp_f32_e32 v119, v17
	v_mul_f32_e32 v12, 0x3e38aa3b, v12
	v_exp_f32_e32 v121, v13
	v_sub_f32_e32 v13, v14, v101
	v_add_f32_e32 v16, v116, v20
	v_exp_f32_e32 v120, v12
	v_mul_f32_e32 v13, 0x3e38aa3b, v13
	v_add_f32_e32 v16, v117, v16
	v_exp_f32_e32 v122, v13
	v_sub_f32_e32 v13, v15, v101
	v_sub_f32_e32 v9, v9, v101
	v_add_f32_e32 v16, v118, v16
	v_mul_f32_e32 v13, 0x3e38aa3b, v13
	v_sub_f32_e32 v8, v8, v101
	v_mul_f32_e32 v9, 0x3e38aa3b, v9
	v_add_f32_e32 v16, v119, v16
	v_exp_f32_e32 v123, v13
	v_mul_f32_e32 v8, 0x3e38aa3b, v8
	v_exp_f32_e32 v125, v9
	v_sub_f32_e32 v9, v10, v101
	v_add_f32_e32 v12, v120, v16
	v_exp_f32_e32 v124, v8
	v_mul_f32_e32 v9, 0x3e38aa3b, v9
	v_add_f32_e32 v12, v121, v12
	v_exp_f32_e32 v126, v9
	v_sub_f32_e32 v9, v11, v101
	v_sub_f32_e32 v5, v5, v101
	v_add_f32_e32 v12, v122, v12
	v_mul_f32_e32 v9, 0x3e38aa3b, v9
	v_sub_f32_e32 v4, v4, v101
	v_mul_f32_e32 v5, 0x3e38aa3b, v5
	v_add_f32_e32 v12, v123, v12
	v_exp_f32_e32 v127, v9
	v_mul_f32_e32 v4, 0x3e38aa3b, v4
	v_exp_f32_e32 v129, v5
	v_sub_f32_e32 v5, v6, v101
	v_add_f32_e32 v8, v124, v12
	v_exp_f32_e32 v128, v4
	v_mul_f32_e32 v5, 0x3e38aa3b, v5
	v_add_f32_e32 v8, v125, v8
	v_exp_f32_e32 v130, v5
	v_sub_f32_e32 v5, v7, v101
	v_sub_f32_e32 v1, v1, v101
	v_add_f32_e32 v8, v126, v8
	v_mul_f32_e32 v5, 0x3e38aa3b, v5
	v_sub_f32_e32 v0, v0, v101
	v_mul_f32_e32 v1, 0x3e38aa3b, v1
	v_add_f32_e32 v8, v127, v8
	v_exp_f32_e32 v131, v5
	v_mul_f32_e32 v0, 0x3e38aa3b, v0
	v_exp_f32_e32 v133, v1
	v_sub_f32_e32 v1, v2, v101
	v_add_f32_e32 v4, v128, v8
	v_exp_f32_e32 v132, v0
	v_mul_f32_e32 v1, 0x3e38aa3b, v1
	v_add_f32_e32 v4, v129, v4
	v_exp_f32_e32 v134, v1
	v_sub_f32_e32 v1, v3, v101
	v_add_f32_e32 v4, v130, v4
	v_mul_f32_e32 v1, 0x3e38aa3b, v1
	v_add_f32_e32 v4, v131, v4
	v_exp_f32_e32 v101, v1
	v_add_f32_e32 v0, v132, v4
	v_add_f32_e32 v0, v133, v0
	v_add_f32_e32 v0, v134, v0
	v_add_f32_e32 v0, v101, v0
	ds_bpermute_b32 v1, v97, v0
	ds_read_b128 v[4:7], v89 offset:32768
	ds_read_b128 v[8:11], v89 offset:40960
	ds_read_b128 v[12:15], v89 offset:49152
	ds_read_b128 v[16:19], v89 offset:57344
	v_cvt_pk_bf16_f32 v2, v104, v105
	v_cvt_pk_bf16_f32 v3, v106, v107
	s_waitcnt lgkmcnt(4)
	v_add_f32_e32 v0, v0, v1
	ds_bpermute_b32 v1, v98, v0
	s_waitcnt lgkmcnt(0)
	v_add_f32_e32 v135, v0, v1
	v_cvt_pk_bf16_f32 v0, v99, v100
	v_cvt_pk_bf16_f32 v1, v102, v103
	s_nop 1
	v_mfma_f32_16x16x32_bf16 v[4:7], v[4:7], v[0:3], 0
	v_mfma_f32_16x16x32_bf16 v[8:11], v[8:11], v[0:3], 0
	v_mfma_f32_16x16x32_bf16 v[12:15], v[12:15], v[0:3], 0
	v_mfma_f32_16x16x32_bf16 v[0:3], v[16:19], v[0:3], 0
	v_cvt_pk_bf16_f32 v16, v52, v53
	v_cvt_pk_bf16_f32 v17, v54, v55
	v_cvt_pk_bf16_f32 v18, v48, v49
	v_cvt_pk_bf16_f32 v19, v50, v51
	ds_read_b128 v[20:23], v90 offset:32768
	ds_read_b128 v[24:27], v90 offset:40960
	ds_read_b128 v[48:51], v90 offset:49152
	ds_read_b128 v[52:55], v90 offset:57344
	s_waitcnt lgkmcnt(3)
	v_mfma_f32_16x16x32_bf16 v[4:7], v[20:23], v[16:19], v[4:7]
	s_waitcnt lgkmcnt(2)
	v_mfma_f32_16x16x32_bf16 v[8:11], v[24:27], v[16:19], v[8:11]
	s_waitcnt lgkmcnt(1)
	v_mfma_f32_16x16x32_bf16 v[12:15], v[48:51], v[16:19], v[12:15]
	s_waitcnt lgkmcnt(0)
	v_mfma_f32_16x16x32_bf16 v[0:3], v[52:55], v[16:19], v[0:3]
	v_cvt_pk_bf16_f32 v16, v44, v45
	v_cvt_pk_bf16_f32 v17, v46, v47
	v_cvt_pk_bf16_f32 v18, v40, v41
	v_cvt_pk_bf16_f32 v19, v42, v43
	ds_read_b128 v[20:23], v91 offset:32768
	ds_read_b128 v[24:27], v91 offset:40960
	ds_read_b128 v[40:43], v91 offset:49152
	ds_read_b128 v[44:47], v91 offset:57344
	s_waitcnt lgkmcnt(3)
	v_mfma_f32_16x16x32_bf16 v[4:7], v[20:23], v[16:19], v[4:7]
	s_waitcnt lgkmcnt(2)
	v_mfma_f32_16x16x32_bf16 v[8:11], v[24:27], v[16:19], v[8:11]
	s_waitcnt lgkmcnt(1)
	v_mfma_f32_16x16x32_bf16 v[12:15], v[40:43], v[16:19], v[12:15]
	s_waitcnt lgkmcnt(0)
	v_mfma_f32_16x16x32_bf16 v[0:3], v[44:47], v[16:19], v[0:3]
	v_cvt_pk_bf16_f32 v16, v36, v37
	v_cvt_pk_bf16_f32 v17, v38, v39
	v_cvt_pk_bf16_f32 v18, v32, v33
	v_cvt_pk_bf16_f32 v19, v34, v35
	ds_read_b128 v[20:23], v92 offset:32768
	ds_read_b128 v[24:27], v92 offset:40960
	ds_read_b128 v[32:35], v92 offset:49152
	ds_read_b128 v[36:39], v92 offset:57344
	s_waitcnt lgkmcnt(3)
	v_mfma_f32_16x16x32_bf16 v[4:7], v[20:23], v[16:19], v[4:7]
	s_waitcnt lgkmcnt(2)
	v_mfma_f32_16x16x32_bf16 v[8:11], v[24:27], v[16:19], v[8:11]
	s_waitcnt lgkmcnt(1)
	v_mfma_f32_16x16x32_bf16 v[12:15], v[32:35], v[16:19], v[12:15]
	s_waitcnt lgkmcnt(0)
	v_mfma_f32_16x16x32_bf16 v[0:3], v[36:39], v[16:19], v[0:3]
	v_cvt_pk_bf16_f32 v16, v28, v29
	v_cvt_pk_bf16_f32 v17, v30, v31
	ds_read_b128 v[20:23], v93 offset:32768
	ds_read_b128 v[24:27], v93 offset:40960
	ds_read_b128 v[28:31], v93 offset:49152
	ds_read_b128 v[32:35], v93 offset:57344
	v_cvt_pk_bf16_f32 v18, v109, v108
	v_cvt_pk_bf16_f32 v19, v110, v111
	s_waitcnt lgkmcnt(3)
	s_nop 0
	v_mfma_f32_16x16x32_bf16 v[4:7], v[20:23], v[16:19], v[4:7]
	s_waitcnt lgkmcnt(2)
	v_mfma_f32_16x16x32_bf16 v[8:11], v[24:27], v[16:19], v[8:11]
	s_waitcnt lgkmcnt(1)
	v_mfma_f32_16x16x32_bf16 v[12:15], v[28:31], v[16:19], v[12:15]
	s_waitcnt lgkmcnt(0)
	v_mfma_f32_16x16x32_bf16 v[0:3], v[32:35], v[16:19], v[0:3]
	ds_read_b128 v[20:23], v94 offset:32768
	ds_read_b128 v[24:27], v94 offset:40960
	ds_read_b128 v[28:31], v94 offset:49152
	ds_read_b128 v[32:35], v94 offset:57344
	v_cvt_pk_bf16_f32 v16, v112, v113
	v_cvt_pk_bf16_f32 v17, v114, v115
	v_cvt_pk_bf16_f32 v18, v116, v117
	v_cvt_pk_bf16_f32 v19, v118, v119
	s_waitcnt lgkmcnt(3)
	s_nop 0
	v_mfma_f32_16x16x32_bf16 v[4:7], v[20:23], v[16:19], v[4:7]
	s_waitcnt lgkmcnt(2)
	v_mfma_f32_16x16x32_bf16 v[8:11], v[24:27], v[16:19], v[8:11]
	s_waitcnt lgkmcnt(1)
	v_mfma_f32_16x16x32_bf16 v[12:15], v[28:31], v[16:19], v[12:15]
	s_waitcnt lgkmcnt(0)
	v_mfma_f32_16x16x32_bf16 v[0:3], v[32:35], v[16:19], v[0:3]
	ds_read_b128 v[20:23], v95 offset:32768
	ds_read_b128 v[24:27], v95 offset:40960
	ds_read_b128 v[28:31], v95 offset:49152
	ds_read_b128 v[32:35], v95 offset:57344
	v_cvt_pk_bf16_f32 v16, v120, v121
	v_cvt_pk_bf16_f32 v17, v122, v123
	v_cvt_pk_bf16_f32 v18, v124, v125
	v_cvt_pk_bf16_f32 v19, v126, v127
	s_waitcnt lgkmcnt(3)
	s_nop 0
	v_mfma_f32_16x16x32_bf16 v[4:7], v[20:23], v[16:19], v[4:7]
	s_waitcnt lgkmcnt(2)
	v_mfma_f32_16x16x32_bf16 v[8:11], v[24:27], v[16:19], v[8:11]
	s_waitcnt lgkmcnt(1)
	v_mfma_f32_16x16x32_bf16 v[12:15], v[28:31], v[16:19], v[12:15]
	s_waitcnt lgkmcnt(0)
	v_mfma_f32_16x16x32_bf16 v[0:3], v[32:35], v[16:19], v[0:3]
	ds_read_b128 v[20:23], v96 offset:32768
	ds_read_b128 v[24:27], v96 offset:40960
	ds_read_b128 v[28:31], v96 offset:49152
	ds_read_b128 v[32:35], v96 offset:57344
	v_cvt_pk_bf16_f32 v16, v128, v129
	v_cvt_pk_bf16_f32 v17, v130, v131
	v_cvt_pk_bf16_f32 v18, v132, v133
	v_cvt_pk_bf16_f32 v19, v134, v101
	s_waitcnt lgkmcnt(3)
	s_nop 0
	v_mfma_f32_16x16x32_bf16 v[4:7], v[20:23], v[16:19], v[4:7]
	s_waitcnt lgkmcnt(2)
	v_mfma_f32_16x16x32_bf16 v[8:11], v[24:27], v[16:19], v[8:11]
	s_waitcnt lgkmcnt(1)
	v_mfma_f32_16x16x32_bf16 v[12:15], v[28:31], v[16:19], v[12:15]
	s_waitcnt lgkmcnt(0)
	v_mfma_f32_16x16x32_bf16 v[0:3], v[32:35], v[16:19], v[0:3]
	v_div_scale_f32 v16, s[12:13], v135, v135, 1.0
	v_rcp_f32_e32 v17, v16
	v_div_scale_f32 v18, vcc, 1.0, v135, 1.0
	s_add_i32 s11, s11, 8
	v_fma_f32 v19, -v16, v17, 1.0
	v_fmac_f32_e32 v17, v19, v17
	v_mul_f32_e32 v19, v18, v17
	v_fma_f32 v20, -v16, v19, v18
	v_fmac_f32_e32 v19, v20, v17
	v_fma_f32 v16, -v16, v19, v18
	v_div_fmas_f32 v16, v16, v17, v19
	v_lshlrev_b64 v[18:19], 11, v[70:71]
	v_lshl_add_u64 v[18:19], s[0:1], 0, v[18:19]
	v_div_fixup_f32 v16, v16, v135, 1.0
	v_lshl_add_u64 v[18:19], v[18:19], 0, s[66:67]
	v_lshl_add_u64 v[18:19], v[18:19], 0, v[160:161]
	v_mul_f32_e32 v6, v6, v16
	v_mul_f32_e32 v7, v7, v16
	v_mul_f32_e32 v4, v4, v16
	v_mul_f32_e32 v5, v5, v16
	v_lshl_add_u64 v[20:21], v[18:19], 0, s[74:75]
	v_cvt_pk_bf16_f32 v4, v4, v5
	v_cvt_pk_bf16_f32 v5, v6, v7
	v_add_co_u32_e32 v6, vcc, s24, v18
	v_mul_f32_e32 v2, v2, v16
	v_mul_f32_e32 v3, v3, v16
	s_nop 0
	v_addc_co_u32_e32 v7, vcc, 0, v19, vcc
	global_store_dwordx2 v[6:7], v[4:5], off offset:1536
	v_mul_f32_e32 v4, v10, v16
	v_mul_f32_e32 v5, v11, v16
	v_mul_f32_e32 v6, v8, v16
	v_mul_f32_e32 v7, v9, v16
	v_mul_f32_e32 v0, v0, v16
	v_mul_f32_e32 v1, v1, v16
	v_cvt_pk_bf16_f32 v6, v6, v7
	v_cvt_pk_bf16_f32 v7, v4, v5
	global_store_dwordx2 v[20:21], v[6:7], off offset:32
	v_mul_f32_e32 v4, v14, v16
	v_mul_f32_e32 v5, v15, v16
	v_mul_f32_e32 v6, v12, v16
	v_mul_f32_e32 v7, v13, v16
	v_cvt_pk_bf16_f32 v0, v0, v1
	v_cvt_pk_bf16_f32 v6, v6, v7
	v_cvt_pk_bf16_f32 v7, v4, v5
	v_cvt_pk_bf16_f32 v1, v2, v3
	s_cmp_gt_i32 s11, 7
	v_add_u32_e32 v70, 0x80, v70
	global_store_dwordx2 v[20:21], v[6:7], off offset:64
	global_store_dwordx2 v[20:21], v[0:1], off offset:96
	s_cbranch_scc0 .LBB0_1769
	s_branch .LBB0_1766
